# MLA loop: K fragment LDS reads issued right behind the barrier, next tile's global K/V prefetch after them (was before)
# speedup vs baseline: 1.0032x; 1.0032x over previous
; #define MFMA(a, b, c) __builtin_amdgcn_mfma_f32_32x32x16_bf16((a), (b), (c), 0, 0, 0)
; DI float xhalf_max(float x) { const auto rr = __builtin_amdgcn_permlane32_swap(__float_as_uint(x), __float_as_uint(x), false, false); return fmaxf(__uint_as_float(rr[0]), __uint_as_float(rr[1])); }
; template <int DQK, int DV, bool BAND> ...
;     ...
;   for (int kt = kt_lo; kt < kt_hi; ++kt) {
;     __syncthreads();
;     if (!PREF) ALOAD(kt);
; #pragma unroll
;     for (int i = 0; i < KCH; ++i) { const int cid = tid + 256 * i, row = cid / KCPR, c8 = cid - row * KCPR; *(u32x4*)&Ks[row * KLD + c8 * 8] = kreg[i]; }
; #pragma unroll
;     for (int i = 0; i < VCH; ++i) { const int cid = tid + 256 * i, row = cid >> 3, c8 = cid & 7;
;       *(u32x2*)&Vs[row * VLD + c8 * 8] = u32x2{vreg[i][0], vreg[i][1]}; *(u32x2*)&Vs[row * VLD + c8 * 8 + 4] = u32x2{vreg[i][2], vreg[i][3]}; }
;     __syncthreads();
;     if (PREF && kt + 1 < kt_hi) ALOAD(kt + 1);
;     if constexpr (DQK < 128) {
;       f32x16 p0, p1;
; #pragma unroll
;       for (int r = 0; r < 16; ++r) { p0[r] = 0.f; p1[r] = 0.f; }
;       __builtin_amdgcn_s_setprio(1);
; #pragma unroll
;       for (int d0 = 0; d0 < ND0; ++d0) {
;         const bf16x8 k0f = *(const bf16x8*)&Ks[r32 * KLD + d0 * 16 + hi * 8];
;         const bf16x8 k1f = *(const bf16x8*)&Ks[(32 + r32) * KLD + d0 * 16 + hi * 8];
;         p0 = MFMA(k0f, qf[d0], p0); p1 = MFMA(k1f, qf[d0], p1);
;       }
;       __builtin_amdgcn_s_setprio(0);
;       float mx = fmaxf(p0[0], p1[0]);
; #pragma unroll
;       for (int r = 1; r < 16; ++r) mx = fmaxf(mx, fmaxf(p0[r], p1[r]));
;       mx = xhalf_max(mx);
;       if (__builtin_amdgcn_ballot_w64(mx > m_run + 8.f) != 0ull) {
;         const float m_new = fmaxf(m_run, mx); const float m_use = (m_new == -INFINITY) ? 0.f : m_new;
;         const float alpha = __builtin_amdgcn_exp2f(m_run - m_use);
;         l_run *= alpha; m_run = m_new;
;         if (hi == 0) sc[r32] = alpha;
;         __builtin_amdgcn_fence(__ATOMIC_RELEASE, "wavefront");
;         __builtin_amdgcn_wave_barrier();
; #pragma unroll
;         for (int g4 = 0; g4 < 4; ++g4) { const f32x4 a4 = *(const f32x4*)&sc[8 * g4 + 4 * hi];
; #pragma unroll
;           for (int cb = 0; cb < NCB; ++cb)
; #pragma unroll
;             for (int j = 0; j < 4; ++j) o[cb][4 * g4 + j] *= a4[j]; }
;         __builtin_amdgcn_wave_barrier();
;       }
.LBB1_320:
	ds_read_b128 v[208:211], v132
	ds_read_b128 v[212:215], v132 offset:6656
	ds_read_b128 v[216:219], v132 offset:32
	ds_read_b128 v[220:223], v132 offset:6688
	ds_read_b128 v[224:227], v132 offset:64
	ds_read_b128 v[228:231], v132 offset:6720
	ds_read_b128 v[232:235], v132 offset:96
	ds_read_b128 v[236:239], v132 offset:6752
	ds_read_b128 v[240:243], v132 offset:128
	ds_read_b128 v[244:247], v132 offset:6784
	ds_read_b128 v[248:251], v132 offset:160
	ds_read_b128 v[134:137], v132 offset:6816
	s_cbranch_scc1 .Lmla_nold
	global_load_dwordx4 v[106:109], v118, s[14:15]
	global_load_dwordx4 v[98:101], v116, s[14:15]
	global_load_dwordx4 v[102:105], v114, s[14:15]
	global_load_dwordx4 v[90:93], v110, s[12:13]
	global_load_dwordx4 v[94:97], v112, s[12:13]
.Lmla_nold:
	s_waitcnt lgkmcnt(11)
	v_mfma_f32_32x32x16_bf16 v[34:49], v[208:211], v[66:69], v[150:165]
	s_waitcnt lgkmcnt(10)
	v_mfma_f32_32x32x16_bf16 v[50:65], v[212:215], v[66:69], v[150:165]
	s_waitcnt lgkmcnt(9)
	v_mfma_f32_32x32x16_bf16 v[34:49], v[216:219], v[70:73], v[34:49]
	s_waitcnt lgkmcnt(8)
	v_mfma_f32_32x32x16_bf16 v[50:65], v[220:223], v[70:73], v[50:65]
	s_waitcnt lgkmcnt(7)
	v_mfma_f32_32x32x16_bf16 v[34:49], v[224:227], v[74:77], v[34:49]
	s_waitcnt lgkmcnt(6)
	v_mfma_f32_32x32x16_bf16 v[50:65], v[228:231], v[74:77], v[50:65]
	s_waitcnt lgkmcnt(5)
	v_mfma_f32_32x32x16_bf16 v[34:49], v[232:235], v[78:81], v[34:49]
	s_waitcnt lgkmcnt(4)
	v_mfma_f32_32x32x16_bf16 v[50:65], v[236:239], v[78:81], v[50:65]
	s_waitcnt lgkmcnt(3)
	v_mfma_f32_32x32x16_bf16 v[34:49], v[240:243], v[82:85], v[34:49]
	s_waitcnt lgkmcnt(2)
	v_mfma_f32_32x32x16_bf16 v[50:65], v[244:247], v[82:85], v[50:65]
	s_waitcnt lgkmcnt(1)
	v_mfma_f32_32x32x16_bf16 v[34:49], v[248:251], v[86:89], v[34:49]
	s_waitcnt lgkmcnt(0)
	v_mfma_f32_32x32x16_bf16 v[50:65], v[134:137], v[86:89], v[50:65]
	ds_read2_b64 v[208:211], v166 offset0:128 offset1:130
	ds_read2_b64 v[212:215], v167 offset0:160 offset1:162
	ds_read2_b64 v[216:219], v166 offset0:136 offset1:138
	ds_read2_b64 v[220:223], v167 offset0:168 offset1:170
	ds_read2_b64 v[224:227], v166 offset0:132 offset1:134
	ds_read2_b64 v[228:231], v167 offset0:164 offset1:166
	ds_read2_b64 v[232:235], v166 offset0:140 offset1:142
	ds_read2_b64 v[236:239], v167 offset0:172 offset1:174
	s_nop 3
	v_max3_f32 v0, v34, v50, v35
	v_max3_f32 v134, v51, v36, v52
	v_max3_f32 v0, v0, v37, v53
	v_max3_f32 v134, v134, v38, v54
	v_max3_f32 v0, v0, v39, v55
	v_max3_f32 v134, v134, v40, v56
	v_max3_f32 v0, v0, v41, v57
	v_max3_f32 v134, v134, v42, v58
	v_max3_f32 v0, v0, v43, v59
	v_max3_f32 v134, v134, v44, v60
	v_max3_f32 v0, v0, v45, v61
	v_max3_f32 v134, v134, v46, v62
	v_max3_f32 v0, v0, v47, v63
	v_max3_f32 v134, v134, v48, v64
	v_max3_f32 v0, v0, v49, v65
	v_max_f32_e32 v0, v0, v134
	v_mov_b32_e32 v134, v0
	s_nop 1
	v_permlane32_swap_b32_e32 v0, v134
	v_max_f32_e32 v0, v0, v134
	v_sub_f32_e32 v0, v0, v150
	v_add_f32_e32 v134, 0x41000000, v133
	v_cmp_gt_f32_e32 vcc, v0, v134
	s_cbranch_vccz .LBB1_324
	v_max_f32_e32 v0, v0, v0
	v_max_f32_e32 v134, v133, v133
	v_max_f32_e32 v0, v134, v0
	v_cmp_neq_f32_e32 vcc, s7, v0
	s_nop 1
	v_cndmask_b32_e32 v134, 0, v0, vcc
	v_sub_f32_e32 v133, v133, v134
	v_exp_f32_e32 v133, v133
	v_add_f32_e32 v168, v150, v134
	s_and_saveexec_b64 s[22:23], s[36:37]
	ds_write_b32 v124, v133 offset:34816
	s_or_b64 exec, exec, s[22:23]
	s_waitcnt lgkmcnt(0)
	ds_read_b128 v[136:139], v120 offset:34816
	ds_read_b128 v[140:143], v120 offset:34848
	ds_read_b128 v[144:147], v120 offset:34880
	ds_read_b128 v[240:243], v120 offset:34912
	v_mul_f32_e32 v126, v126, v133
	v_sub_f32_e32 v34, v34, v168
	v_sub_f32_e32 v35, v35, v168
	v_sub_f32_e32 v36, v36, v168
	v_sub_f32_e32 v37, v37, v168
	v_sub_f32_e32 v38, v38, v168
	v_sub_f32_e32 v39, v39, v168
	v_sub_f32_e32 v40, v40, v168
	v_sub_f32_e32 v41, v41, v168
	v_sub_f32_e32 v42, v42, v168
	v_sub_f32_e32 v43, v43, v168
	v_sub_f32_e32 v44, v44, v168
	v_sub_f32_e32 v45, v45, v168
	v_sub_f32_e32 v46, v46, v168
	v_sub_f32_e32 v47, v47, v168
	v_sub_f32_e32 v48, v48, v168
	v_sub_f32_e32 v49, v49, v168
	v_sub_f32_e32 v50, v50, v168
	v_sub_f32_e32 v51, v51, v168
	v_sub_f32_e32 v52, v52, v168
	v_sub_f32_e32 v53, v53, v168
	v_sub_f32_e32 v54, v54, v168
	v_sub_f32_e32 v55, v55, v168
	v_sub_f32_e32 v56, v56, v168
	v_sub_f32_e32 v57, v57, v168
	v_sub_f32_e32 v58, v58, v168
	v_sub_f32_e32 v59, v59, v168
	v_sub_f32_e32 v60, v60, v168
	v_sub_f32_e32 v61, v61, v168
	v_sub_f32_e32 v62, v62, v168
	v_sub_f32_e32 v63, v63, v168
	v_sub_f32_e32 v64, v64, v168
	v_sub_f32_e32 v65, v65, v168
	v_sub_f32_e32 v150, 0, v134
	v_mov_b32_e32 v151, v150
	v_mov_b32_e32 v152, v150
	v_mov_b32_e32 v153, v150
	v_mov_b32_e32 v154, v150
	v_mov_b32_e32 v155, v150
	v_mov_b32_e32 v156, v150
	v_mov_b32_e32 v157, v150
	v_mov_b32_e32 v158, v150
	v_mov_b32_e32 v159, v150
	v_mov_b32_e32 v160, v150
	v_mov_b32_e32 v161, v150
	v_mov_b32_e32 v162, v150
	v_mov_b32_e32 v163, v150
	v_mov_b32_e32 v164, v150
	v_mov_b32_e32 v165, v150
	s_waitcnt lgkmcnt(0)
	v_pk_mul_f32 v[2:3], v[2:3], v[136:137]
	v_pk_mul_f32 v[4:5], v[4:5], v[138:139]
	v_pk_mul_f32 v[6:7], v[6:7], v[140:141]
	v_pk_mul_f32 v[8:9], v[8:9], v[142:143]
	v_pk_mul_f32 v[10:11], v[10:11], v[144:145]
	v_pk_mul_f32 v[12:13], v[12:13], v[146:147]
	v_pk_mul_f32 v[14:15], v[14:15], v[240:241]
	v_pk_mul_f32 v[16:17], v[16:17], v[242:243]
	v_pk_mul_f32 v[18:19], v[18:19], v[136:137]
	v_pk_mul_f32 v[20:21], v[20:21], v[138:139]
	v_pk_mul_f32 v[22:23], v[22:23], v[140:141]
	v_pk_mul_f32 v[24:25], v[24:25], v[142:143]
	v_pk_mul_f32 v[26:27], v[26:27], v[144:145]
	v_pk_mul_f32 v[28:29], v[28:29], v[146:147]
	v_pk_mul_f32 v[30:31], v[30:31], v[240:241]
	v_pk_mul_f32 v[32:33], v[32:33], v[242:243]
	s_branch .LBB1_325
